# EpiScaleT epilogue: transposed stores delayed one section (same LDS pipelining as EpiScale)
# speedup vs baseline: 1.0046x; 1.0046x over previous
; #define PG8_LAS __attribute__((address_space(3)))
; __device__ __forceinline__ unsigned cvt_pk_bf16(float lo, float hi) { unsigned r; asm volatile("v_cvt_pk_bf16_f32 %0, %1, %2" : "=v"(r) : "v"(lo), "v"(hi)); return r; }
;     __device__ __forceinline__ void operator()(const f32x4 (&acc)[2][2][4][2], const Unit& u, int wr, int wc, int fr, int fq, PG8_LAS unsigned char* lds, int wid, int lane) const {
;     ...
;         asm volatile("s_waitcnt lgkmcnt(0)" ::: "memory"); __builtin_amdgcn_s_barrier(); asm volatile("" ::: "memory");
;         f32x4 cr[2][2];
; #pragma unroll
;         for (int bj = 0; bj < 2; ++bj)
; #pragma unroll
;             for (int n = 0; n < 2; ++n) cr[bj][n] = *(const PG8_LAS f32x4*)(tbl + bj * HALF + wc * 32 + 8 * fq + 4 * n);
;         bf16_t* obase = O + (size_t)(u.pm * BM + wr * 64 + (lane >> 2)) * ldc + u.pn * BM + wc * 32 + 8 * (lane & 3);
; #pragma unroll
;         for (int ai = 0; ai < 2; ++ai)
; #pragma unroll
;             for (int m = 0; m < 4; ++m) {
; #pragma unroll
;                 for (int bj = 0; bj < 2; ++bj) { const f32x4 v0 = acc[ai][bj][m][0] * cr[bj][0], v1 = acc[ai][bj][m][1] * cr[bj][1];
;                     u32x4 w; w.x = cvt_pk_bf16(v0[0], v0[1]); w.y = cvt_pk_bf16(v0[2], v0[3]); w.z = cvt_pk_bf16(v1[0], v1[1]); w.w = cvt_pk_bf16(v1[2], v1[3]);
;                     *(PG8_LAS u32x4*)(st + fr * 80 + fq * 16) = w;
;                     const u32x4 x = *(const PG8_LAS u32x4*)(st + (lane >> 2) * 80 + (lane & 3) * 16);
;                     *(u32x4*)(obase + (size_t)(ai * HALF + m * 16) * ldc + bj * HALF) = x; } }
.LBB0_475:
	s_or_b64 exec, exec, s[40:41]
	s_waitcnt lgkmcnt(0)
	s_barrier
	ds_read_b128 v[148:151], v168
	ds_read_b128 v[144:147], v168 offset:16
	ds_read_b128 v[140:143], v168 offset:512
	ds_read_b128 v[136:139], v168 offset:528
	v_lshl_add_u32 v171, s77, 8, v166
	v_ashrrev_i32_e32 v172, 31, v171
	v_mul_lo_u32 v174, s26, v172
	v_mul_lo_u32 v175, s27, v171
	v_mad_u64_u32 v[172:173], s[0:1], s26, v171, 0
	v_add3_u32 v173, v173, v174, v175
	s_waitcnt lgkmcnt(0)
	v_pk_mul_f32 v[174:175], v[130:131], v[146:147]
	v_pk_mul_f32 v[130:131], v[128:129], v[144:145]
	v_readlane_b32 s0, v252, 45
	v_pk_mul_f32 v[134:135], v[134:135], v[150:151]
	v_pk_mul_f32 v[132:133], v[132:133], v[148:149]
	v_readlane_b32 s1, v252, 46
	v_cvt_pk_bf16_f32 v128, v132, v133
	v_cvt_pk_bf16_f32 v129, v134, v135
	v_cvt_pk_bf16_f32 v130, v130, v131
	v_cvt_pk_bf16_f32 v131, v174, v175
	ds_write_b128 v169, v[128:131]
	ds_read_b128 v[128:131], v170
	v_lshl_add_u64 v[172:173], v[172:173], 1, s[0:1]
	s_ashr_i32 s39, s38, 31
	v_lshl_add_u64 v[132:133], s[38:39], 1, v[172:173]
	v_lshl_add_u64 v[132:133], v[132:133], 0, s[20:21]
	v_lshl_add_u64 v[132:133], v[132:133], 0, v[0:1]
	v_pk_mul_f32 v[126:127], v[126:127], v[142:143]
	v_pk_mul_f32 v[124:125], v[124:125], v[140:141]
	v_pk_mul_f32 v[198:199], v[122:123], v[138:139]
	v_pk_mul_f32 v[122:123], v[120:121], v[136:137]
	v_cvt_pk_bf16_f32 v120, v124, v125
	v_cvt_pk_bf16_f32 v121, v126, v127
	v_pk_mul_f32 v[118:119], v[118:119], v[150:151]
	v_cvt_pk_bf16_f32 v122, v122, v123
	v_cvt_pk_bf16_f32 v123, v198, v199
	ds_write_b128 v169, v[120:123]
	ds_read_b128 v[120:123], v170
	s_waitcnt lgkmcnt(2)
	global_store_dwordx4 v[132:133], v[128:131], off
	v_pk_mul_f32 v[116:117], v[116:117], v[148:149]
	v_pk_mul_f32 v[110:111], v[110:111], v[142:143]
	v_pk_mul_f32 v[108:109], v[108:109], v[140:141]
	v_pk_mul_f32 v[102:103], v[102:103], v[150:151]
	v_pk_mul_f32 v[100:101], v[100:101], v[148:149]
	v_pk_mul_f32 v[94:95], v[94:95], v[142:143]
	v_pk_mul_f32 v[200:201], v[114:115], v[146:147]
	v_pk_mul_f32 v[114:115], v[112:113], v[144:145]
	v_cvt_pk_bf16_f32 v112, v116, v117
	v_cvt_pk_bf16_f32 v113, v118, v119
	v_lshl_add_u64 v[116:117], v[132:133], 0, s[54:55]
	v_cvt_pk_bf16_f32 v114, v114, v115
	v_cvt_pk_bf16_f32 v115, v200, v201
	ds_write_b128 v169, v[112:115]
	ds_read_b128 v[112:115], v170
	s_waitcnt lgkmcnt(2)
	global_store_dwordx4 v[132:133], v[120:123], off offset:256
	v_pk_mul_f32 v[92:93], v[92:93], v[140:141]
	v_pk_mul_f32 v[86:87], v[86:87], v[150:151]
	v_pk_mul_f32 v[84:85], v[84:85], v[148:149]
	v_pk_mul_f32 v[78:79], v[78:79], v[142:143]
	v_pk_mul_f32 v[76:77], v[76:77], v[140:141]
	v_pk_mul_f32 v[70:71], v[70:71], v[150:151]
	v_pk_mul_f32 v[202:203], v[106:107], v[138:139]
	v_pk_mul_f32 v[106:107], v[104:105], v[136:137]
	v_cvt_pk_bf16_f32 v104, v108, v109
	v_cvt_pk_bf16_f32 v105, v110, v111
	v_pk_mul_f32 v[68:69], v[68:69], v[148:149]
	v_cvt_pk_bf16_f32 v106, v106, v107
	v_cvt_pk_bf16_f32 v107, v202, v203
	ds_write_b128 v169, v[104:107]
	ds_read_b128 v[104:107], v170
	s_waitcnt lgkmcnt(2)
	global_store_dwordx4 v[116:117], v[112:115], off
	v_pk_mul_f32 v[62:63], v[62:63], v[142:143]
	v_pk_mul_f32 v[60:61], v[60:61], v[140:141]
	v_pk_mul_f32 v[54:55], v[54:55], v[150:151]
	v_pk_mul_f32 v[52:53], v[52:53], v[148:149]
	v_pk_mul_f32 v[46:47], v[46:47], v[142:143]
	v_pk_mul_f32 v[44:45], v[44:45], v[140:141]
	v_pk_mul_f32 v[204:205], v[98:99], v[146:147]
	v_pk_mul_f32 v[98:99], v[96:97], v[144:145]
	v_cvt_pk_bf16_f32 v96, v100, v101
	v_cvt_pk_bf16_f32 v97, v102, v103
	v_lshl_add_u64 v[100:101], v[116:117], 0, s[54:55]
	v_cvt_pk_bf16_f32 v98, v98, v99
	v_cvt_pk_bf16_f32 v99, v204, v205
	ds_write_b128 v169, v[96:99]
	ds_read_b128 v[96:99], v170
	s_waitcnt lgkmcnt(2)
	global_store_dwordx4 v[116:117], v[104:107], off offset:256
	v_pk_mul_f32 v[38:39], v[38:39], v[150:151]
	v_pk_mul_f32 v[36:37], v[36:37], v[148:149]
	v_pk_mul_f32 v[30:31], v[30:31], v[142:143]
	v_pk_mul_f32 v[28:29], v[28:29], v[140:141]
	v_pk_mul_f32 v[22:23], v[22:23], v[150:151]
	v_pk_mul_f32 v[20:21], v[20:21], v[148:149]
	v_pk_mul_f32 v[198:199], v[90:91], v[138:139]
	v_pk_mul_f32 v[90:91], v[88:89], v[136:137]
	v_cvt_pk_bf16_f32 v88, v92, v93
	v_cvt_pk_bf16_f32 v89, v94, v95
	v_pk_mul_f32 v[14:15], v[14:15], v[142:143]
	v_cvt_pk_bf16_f32 v90, v90, v91
	v_cvt_pk_bf16_f32 v91, v198, v199
	ds_write_b128 v169, v[88:91]
	ds_read_b128 v[88:91], v170
	s_waitcnt lgkmcnt(2)
; #define PG8_LAS __attribute__((address_space(3)))
; __device__ __forceinline__ unsigned cvt_pk_bf16(float lo, float hi) { unsigned r; asm volatile("v_cvt_pk_bf16_f32 %0, %1, %2" : "=v"(r) : "v"(lo), "v"(hi)); return r; }
;     __device__ __forceinline__ void operator()(const f32x4 (&acc)[2][2][4][2], const Unit& u, int wr, int wc, int fr, int fq, PG8_LAS unsigned char* lds, int wid, int lane) const {
;     ...
;         for (int ai = 0; ai < 2; ++ai)
; #pragma unroll
;             for (int m = 0; m < 4; ++m) {
; #pragma unroll
;                 for (int bj = 0; bj < 2; ++bj) { const f32x4 v0 = acc[ai][bj][m][0] * cr[bj][0], v1 = acc[ai][bj][m][1] * cr[bj][1];
;                     u32x4 w; w.x = cvt_pk_bf16(v0[0], v0[1]); w.y = cvt_pk_bf16(v0[2], v0[3]); w.z = cvt_pk_bf16(v1[0], v1[1]); w.w = cvt_pk_bf16(v1[2], v1[3]);
;                     *(PG8_LAS u32x4*)(st + fr * 80 + fq * 16) = w;
;                     const u32x4 x = *(const PG8_LAS u32x4*)(st + (lane >> 2) * 80 + (lane & 3) * 16);
;                     *(u32x4*)(obase + (size_t)(ai * HALF + m * 16) * ldc + bj * HALF) = x; } }
	global_store_dwordx4 v[100:101], v[96:99], off
	v_pk_mul_f32 v[12:13], v[12:13], v[140:141]
	s_and_b64 vcc, exec, s[4:5]
	s_mov_b64 s[0:1], -1
	s_nop 1
	v_pk_mul_f32 v[200:201], v[82:83], v[146:147]
	v_pk_mul_f32 v[82:83], v[80:81], v[144:145]
	v_cvt_pk_bf16_f32 v80, v84, v85
	v_cvt_pk_bf16_f32 v81, v86, v87
	v_lshl_add_u64 v[84:85], v[100:101], 0, s[54:55]
	v_cvt_pk_bf16_f32 v82, v82, v83
	v_cvt_pk_bf16_f32 v83, v200, v201
	ds_write_b128 v169, v[80:83]
	ds_read_b128 v[80:83], v170
	s_waitcnt lgkmcnt(2)
	global_store_dwordx4 v[100:101], v[88:91], off offset:256
	s_nop 1
	v_pk_mul_f32 v[202:203], v[74:75], v[138:139]
	v_pk_mul_f32 v[74:75], v[72:73], v[136:137]
	v_cvt_pk_bf16_f32 v72, v76, v77
	v_cvt_pk_bf16_f32 v73, v78, v79
	s_nop 0
	v_cvt_pk_bf16_f32 v74, v74, v75
	v_cvt_pk_bf16_f32 v75, v202, v203
	ds_write_b128 v169, v[72:75]
	ds_read_b128 v[72:75], v170
	s_waitcnt lgkmcnt(2)
	global_store_dwordx4 v[84:85], v[80:83], off
	s_nop 1
	v_pk_mul_f32 v[204:205], v[66:67], v[146:147]
	v_pk_mul_f32 v[66:67], v[64:65], v[144:145]
	v_cvt_pk_bf16_f32 v64, v68, v69
	v_cvt_pk_bf16_f32 v65, v70, v71
	v_lshl_add_u64 v[68:69], v[84:85], 0, s[16:17]
	v_cvt_pk_bf16_f32 v66, v66, v67
	v_cvt_pk_bf16_f32 v67, v204, v205
	ds_write_b128 v169, v[64:67]
	ds_read_b128 v[64:67], v170
	s_waitcnt lgkmcnt(2)
	global_store_dwordx4 v[84:85], v[72:75], off offset:256
	s_nop 1
	v_pk_mul_f32 v[198:199], v[58:59], v[138:139]
	v_pk_mul_f32 v[58:59], v[56:57], v[136:137]
	v_cvt_pk_bf16_f32 v56, v60, v61
	v_cvt_pk_bf16_f32 v57, v62, v63
	s_nop 0
	v_cvt_pk_bf16_f32 v58, v58, v59
	v_cvt_pk_bf16_f32 v59, v198, v199
	ds_write_b128 v169, v[56:59]
	ds_read_b128 v[56:59], v170
	s_waitcnt lgkmcnt(2)
	global_store_dwordx4 v[68:69], v[64:67], off
	s_nop 1
	v_pk_mul_f32 v[200:201], v[50:51], v[146:147]
	v_pk_mul_f32 v[50:51], v[48:49], v[144:145]
	v_cvt_pk_bf16_f32 v48, v52, v53
	v_cvt_pk_bf16_f32 v49, v54, v55
	v_lshl_add_u64 v[52:53], v[68:69], 0, s[54:55]
	v_cvt_pk_bf16_f32 v50, v50, v51
	v_cvt_pk_bf16_f32 v51, v200, v201
	ds_write_b128 v169, v[48:51]
	ds_read_b128 v[48:51], v170
	s_waitcnt lgkmcnt(2)
	global_store_dwordx4 v[68:69], v[56:59], off offset:256
	s_nop 1
	v_pk_mul_f32 v[202:203], v[42:43], v[138:139]
	v_pk_mul_f32 v[42:43], v[40:41], v[136:137]
	v_cvt_pk_bf16_f32 v40, v44, v45
	v_cvt_pk_bf16_f32 v41, v46, v47
	s_nop 0
	v_cvt_pk_bf16_f32 v42, v42, v43
	v_cvt_pk_bf16_f32 v43, v202, v203
	ds_write_b128 v169, v[40:43]
	ds_read_b128 v[40:43], v170
	s_waitcnt lgkmcnt(2)
	global_store_dwordx4 v[52:53], v[48:51], off
	s_nop 1
	v_pk_mul_f32 v[204:205], v[34:35], v[146:147]
	v_pk_mul_f32 v[34:35], v[32:33], v[144:145]
	v_cvt_pk_bf16_f32 v32, v36, v37
	v_cvt_pk_bf16_f32 v33, v38, v39
	v_lshl_add_u64 v[36:37], v[52:53], 0, s[54:55]
	v_cvt_pk_bf16_f32 v34, v34, v35
	v_cvt_pk_bf16_f32 v35, v204, v205
	ds_write_b128 v169, v[32:35]
	ds_read_b128 v[32:35], v170
	s_waitcnt lgkmcnt(2)
	global_store_dwordx4 v[52:53], v[40:43], off offset:256
	s_nop 1
	v_pk_mul_f32 v[198:199], v[26:27], v[138:139]
	v_pk_mul_f32 v[26:27], v[24:25], v[136:137]
	v_cvt_pk_bf16_f32 v24, v28, v29
	v_cvt_pk_bf16_f32 v25, v30, v31
	s_nop 0
	v_cvt_pk_bf16_f32 v26, v26, v27
	v_cvt_pk_bf16_f32 v27, v198, v199
	ds_write_b128 v169, v[24:27]
	ds_read_b128 v[24:27], v170
	s_waitcnt lgkmcnt(2)
	global_store_dwordx4 v[36:37], v[32:35], off
	s_nop 1
	v_pk_mul_f32 v[200:201], v[18:19], v[146:147]
	v_pk_mul_f32 v[18:19], v[16:17], v[144:145]
	v_cvt_pk_bf16_f32 v16, v20, v21
	v_cvt_pk_bf16_f32 v17, v22, v23
	v_lshl_add_u64 v[20:21], v[36:37], 0, s[54:55]
	v_cvt_pk_bf16_f32 v18, v18, v19
	v_cvt_pk_bf16_f32 v19, v200, v201
	ds_write_b128 v169, v[16:19]
	ds_read_b128 v[16:19], v170
	s_waitcnt lgkmcnt(2)
	global_store_dwordx4 v[36:37], v[24:27], off offset:256
	s_nop 1
	v_pk_mul_f32 v[202:203], v[10:11], v[138:139]
	v_pk_mul_f32 v[10:11], v[8:9], v[136:137]
	v_cvt_pk_bf16_f32 v8, v12, v13
	v_cvt_pk_bf16_f32 v9, v14, v15
	s_nop 0
	v_cvt_pk_bf16_f32 v10, v10, v11
	v_cvt_pk_bf16_f32 v11, v202, v203
	ds_write_b128 v169, v[8:11]
	ds_read_b128 v[8:11], v170
	s_waitcnt lgkmcnt(2)
	global_store_dwordx4 v[20:21], v[16:19], off
	s_waitcnt lgkmcnt(0)
	global_store_dwordx4 v[20:21], v[8:11], off offset:256
	s_cbranch_vccnz .LBB0_455
	s_andn2_b64 vcc, exec, s[10:11]
	s_cbranch_vccnz .LBB0_454
	s_barrier
	s_branch .LBB0_454
